# MLA fast loop: softmax exps moved from end-of-step burst into PV MFMA gaps (pure reschedule)
# speedup vs baseline: 1.0099x; 1.0099x over previous
; #define LAS __attribute__((address_space(3)))
; template <int DK, int PAR, bool HASNEXT, bool LDK, bool LDV, bool STK> ...
;     ...
;     if (STK) { LAS unsigned char* Kn = lds + PAR * A::KBUF; *(LAS u32x4*)(Kn + kl0) = stk0; if (has1) *(LAS u32x4*)(Kn + kl1) = stk1; }
;     if (HASNEXT) { LAS unsigned char* Vn = lds + 2 * A::KBUF + (PAR ^ 1) * A::VBUF; *(LAS u32x4*)(Vn + vl) = stv; }
;     asm volatile("s_waitcnt lgkmcnt(0)\n\ts_barrier" ::: "memory");
; template <int DK>
; __device__ __forceinline__ void attn_unit(LAS unsigned char* lds, const bf16_t* Qp, int qpitch, const bf16_t* Kp, int kpitch, const bf16_t* Vp, int vpitch, bf16_t* Op, int nt) {
;     ...
;     for (; t + 4 < nt; t += 2) {
;         attn_step<DK, 0, true, true, true, true>(ATT_EVEN(cA0, cA1, cB0, cB1, t));
;         attn_step<DK, 1, true, true, true, true>(ATT_ODD(cB0, cB1, cA0, cA1, t + 1));
;     }
.LBB0_762:
	s_or_b64 exec, exec, s[10:11]
	s_waitcnt vmcnt(2)
	ds_write_b128 v170, v[144:147] offset:26624
	s_waitcnt lgkmcnt(0)
	s_barrier
	s_add_i32 s12, s12, 2
	s_mov_b64 s[10:11], 0x30000
	v_lshl_add_u64 v[164:165], v[164:165], 0, s[72:73]
	v_lshl_add_u64 v[166:167], v[166:167], 0, s[72:73]
	s_cmpk_lt_u32 s12, 0x7e
	v_lshl_add_u64 v[168:169], v[168:169], 0, s[10:11]
	s_cbranch_scc0 .LBB0_781

; template <int DK, int PAR, bool HASNEXT, bool LDK, bool LDV, bool STK> ...
;     ...
;     __builtin_amdgcn_s_setprio(1);
;     if (LDK) { ldk0 = *(const u32x4*)(kg0 + (size_t)(t + 3) * kstep); if (has1) ldk1 = *(const u32x4*)(kg1 + (size_t)(t + 3) * kstep); }
;     if (LDV) ldv = *(const u32x4*)(vg + (size_t)(t + 2) * vstep);
;     bf16x8 kf[A::NDS][2];
;     if (HASNEXT) {
; #pragma unroll
;         for (int ds = 0; ds < A::NDS; ++ds) {
;             kf[ds][0] = *(const LAS bf16x8*)(Kb + aoffk + ds * 32);
;             kf[ds][1] = *(const LAS bf16x8*)(Kb + aoffk + 32 * A::KSTR + ds * 32);
;         }
;     }
;     s16x4 vlo[4][2], vhi[4][2];
; #pragma unroll
;     for (int j = 0; j < 2; ++j) {
;         vlo[j][0] = vtr(Vb + aoffv + j * 16 * A::VSTR); vhi[j][0] = vtr(Vb + aoffv + (j * 16 + 8) * A::VSTR);
;         vlo[j][1] = vtr(Vb + aoffv + j * 16 * A::VSTR + 64); vhi[j][1] = vtr(Vb + aoffv + (j * 16 + 8) * A::VSTR + 64);
;     }
;     if (HASNEXT) {
;         f32x16 z;
; #pragma unroll
;         for (int i = 0; i < 16; ++i) z[i] = 0.f;
; #pragma unroll
;         for (int ds = 0; ds < A::NDS; ++ds) {
;             N0 = __builtin_amdgcn_mfma_f32_32x32x16_bf16(kf[ds][0], qf[ds], ds == 0 ? z : N0, 0, 0, 0);
;             N1 = __builtin_amdgcn_mfma_f32_32x32x16_bf16(kf[ds][1], qf[ds], ds == 0 ? z : N1, 0, 0, 0);
;         }
;     }
; #pragma unroll
;     for (int i = 0; i < 16; ++i) { l += C0[i]; l += C1[i]; }
;     bf16x8 pb[4];
;     { u32x4 w;
;       w.x = pk2(C0[0], C0[1]); w.y = pk2(C0[2], C0[3]); w.z = pk2(C0[4], C0[5]); w.w = pk2(C0[6], C0[7]); pb[0] = __builtin_bit_cast(bf16x8, w);
;       w.x = pk2(C0[8], C0[9]); w.y = pk2(C0[10], C0[11]); w.z = pk2(C0[12], C0[13]); w.w = pk2(C0[14], C0[15]); pb[1] = __builtin_bit_cast(bf16x8, w);
;       w.x = pk2(C1[0], C1[1]); w.y = pk2(C1[2], C1[3]); w.z = pk2(C1[4], C1[5]); w.w = pk2(C1[6], C1[7]); pb[2] = __builtin_bit_cast(bf16x8, w);
;       w.x = pk2(C1[8], C1[9]); w.y = pk2(C1[10], C1[11]); w.z = pk2(C1[12], C1[13]); w.w = pk2(C1[14], C1[15]); pb[3] = __builtin_bit_cast(bf16x8, w); }
;     if (HASNEXT) {
;         constexpr int VPER = (DK == 64) ? 6 : 4;
; #pragma unroll
;         for (int g = 0; g < 2 * A::NDS; ++g) { __builtin_amdgcn_sched_group_barrier(0x008, 1, 0); __builtin_amdgcn_sched_group_barrier(0x002, VPER, 0); }
;     }
;     asm volatile("" : "+v"(l));
;     __builtin_amdgcn_sched_barrier(0);
.LBB0_765:
	s_or_b64 exec, exec, s[10:11]
	ds_read_b128 v[32:35], v181 offset:13312
	ds_read_b128 v[50:53], v181 offset:19968
	ds_read_b128 v[68:71], v181 offset:13344
	ds_read_b128 v[196:199], v181 offset:13376
	ds_read_b128 v[200:203], v181 offset:13472
	ds_read_b64_tr_b16 v[204:205], v172 offset:26624
	ds_read_b64_tr_b16 v[206:207], v172 offset:28160
	ds_read_b64_tr_b16 v[212:213], v172 offset:29696
	ds_read_b64_tr_b16 v[214:215], v172 offset:31232
	s_waitcnt lgkmcnt(8)
	v_mfma_f32_32x32x16_bf16 v[32:47], v[32:35], v[120:123], 0
	v_lshl_add_u64 v[80:81], s[50:51], 0, v[168:169]
	v_add_co_u32_e32 v94, vcc, 0x14f30000, v80
	v_add_f32_e32 v96, v185, v48
	s_nop 0
	v_addc_co_u32_e32 v95, vcc, 0, v81, vcc
	global_load_dwordx4 v[144:147], v[94:95], off offset:128
	s_waitcnt lgkmcnt(7)
	v_mfma_f32_32x32x16_bf16 v[48:63], v[50:53], v[120:123], 0
	v_add_f32_e32 v96, v183, v96
	v_add_f32_e32 v96, v187, v96
	v_add_f32_e32 v96, v184, v96
	v_add_f32_e32 v96, v186, v96
	s_waitcnt lgkmcnt(6)
	v_mfma_f32_32x32x16_bf16 v[32:47], v[68:71], v[116:119], v[32:47]
	ds_read_b128 v[68:71], v181 offset:20000
	v_add_f32_e32 v96, v82, v96
	v_add_f32_e32 v96, v189, v96
	v_add_f32_e32 v96, v83, v96
	v_add_f32_e32 v96, v188, v96
	s_waitcnt lgkmcnt(0)
	v_mfma_f32_32x32x16_bf16 v[48:63], v[68:71], v[116:119], v[48:63]
	v_add_f32_e32 v68, v84, v96
	v_add_f32_e32 v68, v190, v68
	v_add_f32_e32 v68, v85, v68
	v_add_f32_e32 v94, v192, v68
	ds_read_b128 v[68:71], v181 offset:20032
	v_mfma_f32_32x32x16_bf16 v[32:47], v[196:199], v[112:115], v[32:47]
	v_add_f32_e32 v94, v86, v94
	v_add_f32_e32 v94, v194, v94
	v_add_f32_e32 v94, v87, v94
	v_add_f32_e32 v94, v191, v94
	ds_read_b128 v[196:199], v181 offset:20096
	s_waitcnt lgkmcnt(1)
	v_mfma_f32_32x32x16_bf16 v[48:63], v[68:71], v[112:115], v[48:63]
	ds_read_b128 v[68:71], v181 offset:13408
	v_add_f32_e32 v94, v72, v94
	v_add_f32_e32 v94, v193, v94
	v_add_f32_e32 v94, v73, v94
	v_add_f32_e32 v94, v88, v94
	s_waitcnt lgkmcnt(0)
	v_mfma_f32_32x32x16_bf16 v[32:47], v[68:71], v[108:111], v[32:47]
	ds_read_b128 v[68:71], v181 offset:20064
	v_add_f32_e32 v94, v74, v94
	v_add_f32_e32 v94, v90, v94
	v_add_f32_e32 v94, v75, v94
	v_add_f32_e32 v94, v89, v94
	s_waitcnt lgkmcnt(0)
	v_mfma_f32_32x32x16_bf16 v[48:63], v[68:71], v[108:111], v[48:63]
	ds_read_b128 v[68:71], v181 offset:13440
	v_add_f32_e32 v94, v76, v94
	v_add_f32_e32 v94, v91, v94
	v_add_f32_e32 v94, v77, v94
	v_add_f32_e32 v94, v92, v94
	s_waitcnt lgkmcnt(0)
	v_mfma_f32_32x32x16_bf16 v[32:47], v[68:71], v[104:107], v[32:47]
	v_add_f32_e32 v94, v78, v94
	ds_read_b128 v[68:71], v181 offset:20128
	v_add_f32_e32 v94, v93, v94
	v_add_f32_e32 v94, v79, v94
	v_cvt_pk_bf16_f32 v208, v185, v187
	v_mfma_f32_32x32x16_bf16 v[48:63], v[196:199], v[104:107], v[48:63]
	v_cvt_pk_bf16_f32 v209, v186, v189
	v_cvt_pk_bf16_f32 v210, v188, v190
	v_cvt_pk_bf16_f32 v211, v192, v194
	v_cvt_pk_bf16_f32 v186, v191, v193
	ds_read_b64_tr_b16 v[196:197], v172 offset:26688
	ds_read_b64_tr_b16 v[198:199], v172 offset:28224
	ds_read_b64_tr_b16 v[190:191], v172 offset:29760
	v_mfma_f32_32x32x16_bf16 v[32:47], v[200:203], v[100:103], v[32:47]
	v_cvt_pk_bf16_f32 v187, v88, v90
	v_cvt_pk_bf16_f32 v188, v89, v91
	v_cvt_pk_bf16_f32 v189, v92, v93
	v_cvt_pk_bf16_f32 v88, v183, v184
	ds_read_b64_tr_b16 v[192:193], v172 offset:31296
	s_waitcnt lgkmcnt(4)
	v_mfma_f32_32x32x16_bf16 v[48:63], v[68:71], v[100:103], v[48:63]
	v_cvt_pk_bf16_f32 v89, v82, v83
	v_cvt_pk_bf16_f32 v90, v84, v85
	v_cvt_pk_bf16_f32 v91, v86, v87
	v_cvt_pk_bf16_f32 v68, v72, v73
	v_cvt_pk_bf16_f32 v69, v74, v75
	v_cvt_pk_bf16_f32 v70, v76, v77
	v_cvt_pk_bf16_f32 v71, v78, v79
	v_mfma_f32_32x32x16_bf16 v[16:31], v[204:207], v[208:211], v[16:31]
	ds_read_b64_tr_b16 v[72:73], v172 offset:32768
	ds_read_b64_tr_b16 v[74:75], v172 offset:34304
	ds_read_b64_tr_b16 v[76:77], v172 offset:32832
	ds_read_b64_tr_b16 v[78:79], v172 offset:34368
	v_exp_f32_e32 v96, v32
	v_exp_f32_e32 v99, v33
	v_exp_f32_e32 v150, v34
	v_exp_f32_e32 v152, v35
	s_waitcnt lgkmcnt(6)
	v_mfma_f32_32x32x16_bf16 v[0:15], v[196:199], v[208:211], v[0:15]
	v_exp_f32_e32 v154, v36
	v_exp_f32_e32 v184, v39
	v_exp_f32_e32 v185, v40
	v_exp_f32_e32 v195, v47
	v_mfma_f32_32x32x16_bf16 v[16:31], v[212:215], v[186:189], v[16:31]
	v_exp_f32_e32 v155, v52
	v_exp_f32_e32 v52, v37
	v_exp_f32_e32 v180, v53
	v_exp_f32_e32 v53, v38
	s_waitcnt lgkmcnt(4)
	v_mfma_f32_32x32x16_bf16 v[0:15], v[190:193], v[186:189], v[0:15]
	v_exp_f32_e32 v98, v48
	v_exp_f32_e32 v49, v49
	v_exp_f32_e32 v151, v50
	v_exp_f32_e32 v153, v51
	s_waitcnt lgkmcnt(2)
	v_mfma_f32_32x32x16_bf16 v[16:31], v[72:75], v[88:91], v[16:31]
	ds_read_b64_tr_b16 v[72:73], v172 offset:35840
	ds_read_b64_tr_b16 v[74:75], v172 offset:37376
	v_exp_f32_e32 v183, v54
	v_exp_f32_e32 v187, v55
	v_exp_f32_e32 v188, v56
	v_exp_f32_e32 v56, v41
	s_waitcnt lgkmcnt(2)
	v_mfma_f32_32x32x16_bf16 v[0:15], v[76:79], v[88:91], v[0:15]
	ds_read_b64_tr_b16 v[76:77], v172 offset:35904
	ds_read_b64_tr_b16 v[78:79], v172 offset:37440
	v_exp_f32_e32 v189, v57
	v_exp_f32_e32 v57, v42
	v_exp_f32_e32 v190, v58
	v_exp_f32_e32 v186, v43
	s_waitcnt lgkmcnt(2)
	v_mfma_f32_32x32x16_bf16 v[16:31], v[72:75], v[68:71], v[16:31]
	v_exp_f32_e32 v191, v59
	v_exp_f32_e32 v192, v44
	v_exp_f32_e32 v193, v60
	v_exp_f32_e32 v60, v45
	s_waitcnt lgkmcnt(0)
	v_mfma_f32_32x32x16_bf16 v[0:15], v[76:79], v[68:71], v[0:15]
	v_exp_f32_e32 v194, v61
	v_exp_f32_e32 v61, v46
	v_exp_f32_e32 v62, v62
	v_exp_f32_e32 v63, v63
	s_setprio 0
	s_waitcnt vmcnt(3)
	ds_write_b128 v173, v[132:135]
	s_and_saveexec_b64 s[10:11], s[6:7]
	ds_write_b128 v182, v[128:131]
	s_or_b64 exec, exec, s[10:11]
	s_waitcnt vmcnt(2)
	ds_write_b128 v170, v[136:139] offset:38912
	s_waitcnt lgkmcnt(0)
	s_barrier
	s_setprio 1
	v_add_co_u32_e32 v66, vcc, 0x2a5a8000, v66
	s_nop 1
	v_addc_co_u32_e32 v67, vcc, 0, v67, vcc
	global_load_dwordx4 v[132:135], v[66:67], off
	s_and_saveexec_b64 s[10:11], s[6:7]
	s_cbranch_execz .LBB0_769
	v_add_co_u32_e32 v64, vcc, 0x2a5a8000, v64
	s_nop 1
	v_addc_co_u32_e32 v65, vcc, 0, v65, vcc
	global_load_dwordx4 v[128:131], v[64:65], off
; template <int DK, int PAR, bool HASNEXT, bool LDK, bool LDV, bool STK> ...
;     ...
;     __builtin_amdgcn_s_setprio(1);
;     if (LDK) { ldk0 = *(const u32x4*)(kg0 + (size_t)(t + 3) * kstep); if (has1) ldk1 = *(const u32x4*)(kg1 + (size_t)(t + 3) * kstep); }
;     if (LDV) ldv = *(const u32x4*)(vg + (size_t)(t + 2) * vstep);
;     bf16x8 kf[A::NDS][2];
;     if (HASNEXT) {
; #pragma unroll
;         for (int ds = 0; ds < A::NDS; ++ds) {
;             kf[ds][0] = *(const LAS bf16x8*)(Kb + aoffk + ds * 32);
;             kf[ds][1] = *(const LAS bf16x8*)(Kb + aoffk + 32 * A::KSTR + ds * 32);
;         }
;     }
;     s16x4 vlo[4][2], vhi[4][2];
; #pragma unroll
;     for (int j = 0; j < 2; ++j) {
;         vlo[j][0] = vtr(Vb + aoffv + j * 16 * A::VSTR); vhi[j][0] = vtr(Vb + aoffv + (j * 16 + 8) * A::VSTR);
;         vlo[j][1] = vtr(Vb + aoffv + j * 16 * A::VSTR + 64); vhi[j][1] = vtr(Vb + aoffv + (j * 16 + 8) * A::VSTR + 64);
;     }
;     if (HASNEXT) {
;         f32x16 z;
; #pragma unroll
;         for (int i = 0; i < 16; ++i) z[i] = 0.f;
; #pragma unroll
;         for (int ds = 0; ds < A::NDS; ++ds) {
;             N0 = __builtin_amdgcn_mfma_f32_32x32x16_bf16(kf[ds][0], qf[ds], ds == 0 ? z : N0, 0, 0, 0);
;             N1 = __builtin_amdgcn_mfma_f32_32x32x16_bf16(kf[ds][1], qf[ds], ds == 0 ? z : N1, 0, 0, 0);
;         }
;     }
; #pragma unroll
;     for (int i = 0; i < 16; ++i) { l += C0[i]; l += C1[i]; }
;     bf16x8 pb[4];
;     { u32x4 w;
;       w.x = pk2(C0[0], C0[1]); w.y = pk2(C0[2], C0[3]); w.z = pk2(C0[4], C0[5]); w.w = pk2(C0[6], C0[7]); pb[0] = __builtin_bit_cast(bf16x8, w);
;       w.x = pk2(C0[8], C0[9]); w.y = pk2(C0[10], C0[11]); w.z = pk2(C0[12], C0[13]); w.w = pk2(C0[14], C0[15]); pb[1] = __builtin_bit_cast(bf16x8, w);
;       w.x = pk2(C1[0], C1[1]); w.y = pk2(C1[2], C1[3]); w.z = pk2(C1[4], C1[5]); w.w = pk2(C1[6], C1[7]); pb[2] = __builtin_bit_cast(bf16x8, w);
;       w.x = pk2(C1[8], C1[9]); w.y = pk2(C1[10], C1[11]); w.z = pk2(C1[12], C1[13]); w.w = pk2(C1[14], C1[15]); pb[3] = __builtin_bit_cast(bf16x8, w); }
;     if (HASNEXT) {
;         constexpr int VPER = (DK == 64) ? 6 : 4;
; #pragma unroll
;         for (int g = 0; g < 2 * A::NDS; ++g) { __builtin_amdgcn_sched_group_barrier(0x008, 1, 0); __builtin_amdgcn_sched_group_barrier(0x002, VPER, 0); }
;     }
;     asm volatile("" : "+v"(l));
;     __builtin_amdgcn_sched_barrier(0);
.LBB0_769:
	s_or_b64 exec, exec, s[10:11]
	ds_read_b128 v[32:35], v181
	s_mov_b32 s10, 0x14f48000
	s_waitcnt lgkmcnt(0)
	v_mfma_f32_32x32x16_bf16 v[64:79], v[32:35], v[120:123], 0
	v_add_co_u32_e32 v40, vcc, s10, v80
	s_nop 0
	v_addc_co_u32_e32 v41, vcc, 0, v81, vcc
	global_load_dwordx4 v[136:139], v[40:41], off offset:128
	ds_read_b128 v[36:39], v181 offset:6656
	ds_read_b128 v[32:35], v181 offset:32
	v_add_f32_e32 v48, v96, v94
	v_add_f32_e32 v48, v98, v48
	s_waitcnt lgkmcnt(1)
	v_mfma_f32_32x32x16_bf16 v[80:95], v[36:39], v[120:123], 0
	ds_read_b128 v[36:39], v181 offset:6688
	v_add_f32_e32 v40, v99, v48
	v_add_f32_e32 v40, v49, v40
	v_add_f32_e32 v40, v150, v40
	v_add_f32_e32 v40, v151, v40
	s_waitcnt lgkmcnt(1)
	v_mfma_f32_32x32x16_bf16 v[64:79], v[32:35], v[116:119], v[64:79]
	ds_read_b128 v[32:35], v181 offset:64
	v_add_f32_e32 v40, v152, v40
	v_add_f32_e32 v40, v153, v40
	v_add_f32_e32 v40, v154, v40
	v_add_f32_e32 v40, v155, v40
	s_waitcnt lgkmcnt(1)
	v_mfma_f32_32x32x16_bf16 v[80:95], v[36:39], v[116:119], v[80:95]
	ds_read_b128 v[36:39], v181 offset:6720
	v_add_f32_e32 v40, v52, v40
	v_add_f32_e32 v40, v180, v40
	v_add_f32_e32 v40, v53, v40
	v_add_f32_e32 v40, v183, v40
	s_waitcnt lgkmcnt(1)
	v_mfma_f32_32x32x16_bf16 v[64:79], v[32:35], v[112:115], v[64:79]
	ds_read_b128 v[32:35], v181 offset:96
	v_add_f32_e32 v40, v184, v40
	v_add_f32_e32 v40, v187, v40
	v_add_f32_e32 v40, v185, v40
	v_add_f32_e32 v40, v188, v40
	s_waitcnt lgkmcnt(1)
	v_mfma_f32_32x32x16_bf16 v[80:95], v[36:39], v[112:115], v[80:95]
	ds_read_b128 v[36:39], v181 offset:6752
	v_add_f32_e32 v40, v56, v40
	v_add_f32_e32 v40, v189, v40
	v_add_f32_e32 v40, v57, v40
	v_add_f32_e32 v40, v190, v40
	s_waitcnt lgkmcnt(1)
	v_mfma_f32_32x32x16_bf16 v[64:79], v[32:35], v[108:111], v[64:79]
	v_add_f32_e32 v40, v186, v40
	v_add_f32_e32 v40, v191, v40
	ds_read_b128 v[32:35], v181 offset:128
	v_add_f32_e32 v40, v192, v40
	v_add_f32_e32 v44, v193, v40
	s_waitcnt lgkmcnt(1)
	v_mfma_f32_32x32x16_bf16 v[80:95], v[36:39], v[108:111], v[80:95]
	ds_read_b128 v[36:39], v181 offset:6784
	v_add_f32_e32 v44, v60, v44
	v_add_f32_e32 v44, v194, v44
	v_add_f32_e32 v44, v61, v44
	v_add_f32_e32 v48, v62, v44
	ds_read_b128 v[40:43], v181 offset:160
	s_waitcnt lgkmcnt(2)
	v_mfma_f32_32x32x16_bf16 v[64:79], v[32:35], v[104:107], v[64:79]
	ds_read_b128 v[32:35], v181 offset:6816
	v_add_f32_e32 v48, v195, v48
	v_add_f32_e32 v48, v63, v48
	v_cvt_pk_bf16_f32 v50, v96, v99
	v_cvt_pk_bf16_f32 v51, v150, v152
	ds_read_b64_tr_b16 v[44:45], v172 offset:38912
	ds_read_b64_tr_b16 v[46:47], v172 offset:40448
	s_waitcnt lgkmcnt(4)
	v_mfma_f32_32x32x16_bf16 v[80:95], v[36:39], v[104:107], v[80:95]
	v_cvt_pk_bf16_f32 v52, v154, v52
	v_cvt_pk_bf16_f32 v53, v53, v184
	v_cvt_pk_bf16_f32 v58, v185, v56
	v_cvt_pk_bf16_f32 v59, v57, v186
	ds_read_b64_tr_b16 v[36:37], v172 offset:38976
	ds_read_b64_tr_b16 v[38:39], v172 offset:40512
	ds_read_b64_tr_b16 v[54:55], v172 offset:41984
	s_waitcnt lgkmcnt(6)
	v_mfma_f32_32x32x16_bf16 v[64:79], v[40:43], v[100:103], v[64:79]
	v_cvt_pk_bf16_f32 v60, v192, v60
	v_cvt_pk_bf16_f32 v61, v61, v195
	v_cvt_pk_bf16_f32 v184, v98, v49
	v_cvt_pk_bf16_f32 v185, v151, v153
	ds_read_b64_tr_b16 v[56:57], v172 offset:43520
	ds_read_b64_tr_b16 v[40:41], v172 offset:42048
	ds_read_b64_tr_b16 v[42:43], v172 offset:43584
	s_waitcnt lgkmcnt(8)
	v_mfma_f32_32x32x16_bf16 v[80:95], v[32:35], v[100:103], v[80:95]
	v_cvt_pk_bf16_f32 v186, v155, v180
	v_cvt_pk_bf16_f32 v187, v183, v187
	v_cvt_pk_bf16_f32 v32, v188, v189
	v_cvt_pk_bf16_f32 v33, v190, v191
	v_cvt_pk_bf16_f32 v34, v193, v194
	v_cvt_pk_bf16_f32 v35, v62, v63
	s_waitcnt lgkmcnt(6)
	v_mfma_f32_32x32x16_bf16 v[16:31], v[44:47], v[50:53], v[16:31]
	v_exp_f32_e32 v189, v67
	v_exp_f32_e32 v188, v68
	v_exp_f32_e32 v190, v69
	v_exp_f32_e32 v192, v70
	s_waitcnt lgkmcnt(4)
	v_mfma_f32_32x32x16_bf16 v[0:15], v[36:39], v[50:53], v[0:15]
	ds_read_b64_tr_b16 v[36:37], v172 offset:45056
	ds_read_b64_tr_b16 v[38:39], v172 offset:46592
	v_exp_f32_e32 v194, v71
	v_exp_f32_e32 v191, v72
	v_exp_f32_e32 v193, v73
	v_exp_f32_e32 v183, v80
	s_waitcnt lgkmcnt(4)
	v_mfma_f32_32x32x16_bf16 v[16:31], v[54:57], v[58:61], v[16:31]
	v_exp_f32_e32 v82, v82
	v_exp_f32_e32 v83, v83
	v_exp_f32_e32 v84, v84
	v_exp_f32_e32 v85, v85
	s_waitcnt lgkmcnt(2)
	v_mfma_f32_32x32x16_bf16 v[0:15], v[40:43], v[58:61], v[0:15]
	ds_read_b64_tr_b16 v[40:41], v172 offset:45120
	ds_read_b64_tr_b16 v[42:43], v172 offset:46656
	v_exp_f32_e32 v86, v86
	v_exp_f32_e32 v87, v87
	v_exp_f32_e32 v72, v88
	v_exp_f32_e32 v73, v89
	s_waitcnt lgkmcnt(2)
	v_mfma_f32_32x32x16_bf16 v[16:31], v[36:39], v[184:187], v[16:31]
	ds_read_b64_tr_b16 v[36:37], v172 offset:48128
	ds_read_b64_tr_b16 v[38:39], v172 offset:49664
	v_exp_f32_e32 v88, v74
	v_exp_f32_e32 v74, v90
	v_exp_f32_e32 v90, v75
	v_exp_f32_e32 v75, v91
	s_waitcnt lgkmcnt(2)
	v_mfma_f32_32x32x16_bf16 v[0:15], v[40:43], v[184:187], v[0:15]
	ds_read_b64_tr_b16 v[40:41], v172 offset:48192
	ds_read_b64_tr_b16 v[42:43], v172 offset:49728
	v_exp_f32_e32 v89, v76
	v_exp_f32_e32 v76, v92
	v_exp_f32_e32 v91, v77
	v_exp_f32_e32 v77, v93
	s_waitcnt lgkmcnt(2)
	v_mfma_f32_32x32x16_bf16 v[16:31], v[36:39], v[32:35], v[16:31]
	v_exp_f32_e32 v92, v78
	v_exp_f32_e32 v78, v94
	v_exp_f32_e32 v93, v79
	v_exp_f32_e32 v79, v95
	s_waitcnt lgkmcnt(0)
	v_mfma_f32_32x32x16_bf16 v[0:15], v[40:43], v[32:35], v[0:15]
	v_exp_f32_e32 v185, v64
	v_exp_f32_e32 v187, v65
	v_exp_f32_e32 v184, v81
	v_exp_f32_e32 v186, v66
	s_setprio 0
	s_waitcnt vmcnt(3)
	ds_write_b128 v173, v[140:143] offset:13312
	s_and_saveexec_b64 s[10:11], s[6:7]
	s_cbranch_execz .LBB0_762
	ds_write_b128 v182, v[124:127] offset:13312
	s_branch .LBB0_762
